# plus phase-8 GroupNorm row loop software-pipelined (next iteration's loads issued before this iteration's arithmetic)
# baseline (speedup 1.0000x reference)
.LBB0_1304:
	v_add_u32_e32 v12, 1, v8
	v_mad_i64_i32 v[34:35], s[6:7], v12, s77, v[4:5]
	v_add_u32_e32 v14, 2, v8
	v_add_co_u32_e64 v46, s[8:9], s3, v34
	v_mad_i64_i32 v[36:37], s[6:7], v14, s77, v[4:5]
	s_nop 0
	v_addc_co_u32_e64 v47, s[8:9], 0, v35, s[8:9]
	v_mad_i64_i32 v[10:11], s[6:7], v8, s77, v[4:5]
	v_add_u32_e32 v16, 3, v8
	v_add_co_u32_e64 v48, s[8:9], s3, v36
	v_add_co_u32_e32 v32, vcc, 0x1000, v10
	v_mad_i64_i32 v[38:39], s[6:7], v16, s77, v[4:5]
	v_addc_co_u32_e64 v49, s[8:9], 0, v37, s[8:9]
	v_ashrrev_i32_e32 v9, 31, v8
	v_and_b32_e32 v62, 0x1ff, v19
	v_addc_co_u32_e32 v33, vcc, 0, v11, vcc
	v_add_co_u32_e64 v50, s[8:9], s3, v38
	v_lshlrev_b64 v[30:31], 12, v[8:9]
	global_load_dword v9, v[10:11], off
	global_load_dword v63, v[32:33], off
	v_cmp_ne_u32_e64 s[6:7], 0, v62
	v_addc_co_u32_e64 v51, s[8:9], 0, v39, s[8:9]
	global_load_dword v64, v[46:47], off offset:-4096
	global_load_dword v65, v[46:47], off
	global_load_dword v66, v[48:49], off offset:-4096
	global_load_dword v67, v[48:49], off
	global_load_dword v68, v[50:51], off offset:-4096
	global_load_dword v69, v[50:51], off
	v_ashrrev_i32_e32 v13, 31, v12
	v_ashrrev_i32_e32 v17, 31, v16
	v_subbrev_co_u32_e64 v41, s[6:7], 0, v8, s[6:7]
	v_add_co_u32_e32 v40, vcc, 0x2000, v10
	v_ashrrev_i32_e32 v15, 31, v14
	v_lshlrev_b64 v[12:13], 12, v[12:13]
	v_lshlrev_b64 v[16:17], 12, v[16:17]
	v_mad_i64_i32 v[52:53], s[8:9], v41, s77, v[4:5]
	v_addc_co_u32_e32 v41, vcc, 0, v11, vcc
	v_lshl_add_u64 v[42:43], v[0:1], 0, v[30:31]
	v_lshl_add_u64 v[44:45], v[6:7], 0, v[30:31]
	v_lshlrev_b64 v[14:15], 12, v[14:15]
	v_lshl_add_u64 v[32:33], v[0:1], 0, v[12:13]
	v_lshl_add_u64 v[54:55], v[6:7], 0, v[12:13]
	v_lshl_add_u64 v[48:49], v[6:7], 0, v[16:17]
	v_add_co_u32_e32 v50, vcc, s3, v52
	v_lshl_add_u64 v[56:57], v[0:1], 0, v[14:15]
	v_lshl_add_u64 v[58:59], v[6:7], 0, v[14:15]
	v_lshl_add_u64 v[46:47], v[0:1], 0, v[16:17]
	v_addc_co_u32_e32 v51, vcc, 0, v53, vcc
	v_lshl_add_u64 v[60:61], v[2:3], 0, v[12:13]
	v_lshl_add_u64 v[12:13], v[2:3], 0, v[14:15]
	v_lshl_add_u64 v[10:11], v[2:3], 0, v[16:17]
	global_load_ushort v14, v[44:45], off
	global_load_ushort v15, v[44:45], off offset:2048
	global_load_ushort v16, v[54:55], off
	global_load_ushort v17, v[54:55], off offset:2048
	s_nop 0
	global_load_ushort v44, v[58:59], off
	global_load_ushort v45, v[58:59], off offset:2048
	global_load_ushort v54, v[48:49], off
	s_nop 0
	global_load_ushort v48, v[48:49], off offset:2048
	s_nop 0
	global_load_dword v49, v[52:53], off
	s_nop 0
	global_load_dword v52, v[50:51], off offset:-4096
	s_nop 0
	global_load_dword v50, v[50:51], off
	s_nop 0
	global_load_dword v42, v[42:43], off
	s_nop 0
	global_load_dword v34, v[34:35], off
	s_nop 0
	global_load_dword v35, v[40:41], off
	s_nop 0
	global_load_dword v32, v[32:33], off
	s_nop 0
	global_load_dword v33, v[36:37], off
	s_nop 0
	global_load_dword v36, v[56:57], off
	global_load_dword v37, v[38:39], off
	s_nop 0
	global_load_dword v38, v[46:47], off
	v_cmp_eq_u32_e32 vcc, 0, v62
	v_add_u32_e32 v19, s75, v19
	v_cmp_lt_i32_e64 s[6:7], s79, v19
	s_or_b64 s[68:69], s[6:7], s[68:69]
	v_lshl_add_u64 v[30:31], v[2:3], 0, v[30:31]
	v_add_u32_e32 v8, s76, v8
	s_nop 1
	s_mov_b64 s[90:91], vcc
	s_mov_b32 s88, 0
.Lgn_loop:
	s_waitcnt vmcnt(0)
	s_mov_b64 s[92:93], s[90:91]
	v_mov_b32_e32 v71, v9
	v_mov_b32_e32 v72, v10
	v_mov_b32_e32 v73, v11
	v_mov_b32_e32 v74, v12
	v_mov_b32_e32 v75, v13
	v_mov_b32_e32 v76, v14
	v_mov_b32_e32 v77, v15
	v_mov_b32_e32 v78, v16
	v_mov_b32_e32 v79, v17
	v_mov_b32_e32 v92, v30
	v_mov_b32_e32 v93, v31
	v_mov_b32_e32 v94, v32
	v_mov_b32_e32 v95, v33
	v_mov_b32_e32 v96, v34
	v_mov_b32_e32 v97, v35
	v_mov_b32_e32 v98, v36
	v_mov_b32_e32 v99, v37
	v_mov_b32_e32 v100, v38
	v_mov_b32_e32 v104, v42
	v_mov_b32_e32 v106, v44
	v_mov_b32_e32 v107, v45
	v_mov_b32_e32 v110, v48
	v_mov_b32_e32 v111, v49
	v_mov_b32_e32 v112, v50
	v_mov_b32_e32 v114, v52
	v_mov_b32_e32 v116, v54
	v_mov_b32_e32 v122, v60
	v_mov_b32_e32 v123, v61
	v_mov_b32_e32 v125, v63
	v_mov_b32_e32 v126, v64
	v_mov_b32_e32 v127, v65
	v_mov_b32_e32 v128, v66
	v_mov_b32_e32 v129, v67
	v_mov_b32_e32 v130, v68
	v_mov_b32_e32 v131, v69
	v_add_u32_e32 v12, 1, v8
	v_mad_i64_i32 v[34:35], s[6:7], v12, s77, v[4:5]
	v_add_u32_e32 v14, 2, v8
	v_add_co_u32_e64 v46, s[8:9], s3, v34
	v_mad_i64_i32 v[36:37], s[6:7], v14, s77, v[4:5]
	s_nop 0
	v_addc_co_u32_e64 v47, s[8:9], 0, v35, s[8:9]
	v_mad_i64_i32 v[10:11], s[6:7], v8, s77, v[4:5]
	v_add_u32_e32 v16, 3, v8
	v_add_co_u32_e64 v48, s[8:9], s3, v36
	v_add_co_u32_e32 v32, vcc, 0x1000, v10
	v_mad_i64_i32 v[38:39], s[6:7], v16, s77, v[4:5]
	v_addc_co_u32_e64 v49, s[8:9], 0, v37, s[8:9]
	v_ashrrev_i32_e32 v9, 31, v8
	v_and_b32_e32 v62, 0x1ff, v19
	v_addc_co_u32_e32 v33, vcc, 0, v11, vcc
	v_add_co_u32_e64 v50, s[8:9], s3, v38
	v_lshlrev_b64 v[30:31], 12, v[8:9]
	global_load_dword v9, v[10:11], off
	global_load_dword v63, v[32:33], off
	v_cmp_ne_u32_e64 s[6:7], 0, v62
	v_addc_co_u32_e64 v51, s[8:9], 0, v39, s[8:9]
	global_load_dword v64, v[46:47], off offset:-4096
	global_load_dword v65, v[46:47], off
	global_load_dword v66, v[48:49], off offset:-4096
	global_load_dword v67, v[48:49], off
	global_load_dword v68, v[50:51], off offset:-4096
	global_load_dword v69, v[50:51], off
	v_ashrrev_i32_e32 v13, 31, v12
	v_ashrrev_i32_e32 v17, 31, v16
	v_subbrev_co_u32_e64 v41, s[6:7], 0, v8, s[6:7]
	v_add_co_u32_e32 v40, vcc, 0x2000, v10
	v_ashrrev_i32_e32 v15, 31, v14
	v_lshlrev_b64 v[12:13], 12, v[12:13]
	v_lshlrev_b64 v[16:17], 12, v[16:17]
	v_mad_i64_i32 v[52:53], s[8:9], v41, s77, v[4:5]
	v_addc_co_u32_e32 v41, vcc, 0, v11, vcc
	v_lshl_add_u64 v[42:43], v[0:1], 0, v[30:31]
	v_lshl_add_u64 v[44:45], v[6:7], 0, v[30:31]
	v_lshlrev_b64 v[14:15], 12, v[14:15]
	v_lshl_add_u64 v[32:33], v[0:1], 0, v[12:13]
	v_lshl_add_u64 v[54:55], v[6:7], 0, v[12:13]
	v_lshl_add_u64 v[48:49], v[6:7], 0, v[16:17]
	v_add_co_u32_e32 v50, vcc, s3, v52
	v_lshl_add_u64 v[56:57], v[0:1], 0, v[14:15]
	v_lshl_add_u64 v[58:59], v[6:7], 0, v[14:15]
	v_lshl_add_u64 v[46:47], v[0:1], 0, v[16:17]
	v_addc_co_u32_e32 v51, vcc, 0, v53, vcc
	v_lshl_add_u64 v[60:61], v[2:3], 0, v[12:13]
	v_lshl_add_u64 v[12:13], v[2:3], 0, v[14:15]
	v_lshl_add_u64 v[10:11], v[2:3], 0, v[16:17]
	global_load_ushort v14, v[44:45], off
	global_load_ushort v15, v[44:45], off offset:2048
	global_load_ushort v16, v[54:55], off
	global_load_ushort v17, v[54:55], off offset:2048
	s_nop 0
	global_load_ushort v44, v[58:59], off
	global_load_ushort v45, v[58:59], off offset:2048
	global_load_ushort v54, v[48:49], off
	s_nop 0
	global_load_ushort v48, v[48:49], off offset:2048
	s_nop 0
	global_load_dword v49, v[52:53], off
	s_nop 0
	global_load_dword v52, v[50:51], off offset:-4096
	s_nop 0
	global_load_dword v50, v[50:51], off
	s_nop 0
	global_load_dword v42, v[42:43], off
	s_nop 0
	global_load_dword v34, v[34:35], off
	s_nop 0
	global_load_dword v35, v[40:41], off
	s_nop 0
	global_load_dword v32, v[32:33], off
	s_nop 0
	global_load_dword v33, v[36:37], off
	s_nop 0
	global_load_dword v36, v[56:57], off
	global_load_dword v37, v[38:39], off
	s_nop 0
	global_load_dword v38, v[46:47], off
	v_cmp_eq_u32_e32 vcc, 0, v62
	v_add_u32_e32 v19, s75, v19
	v_cmp_lt_i32_e64 s[6:7], s79, v19
	s_or_b64 s[68:69], s[6:7], s[68:69]
	v_lshl_add_u64 v[30:31], v[2:3], 0, v[30:31]
	v_add_u32_e32 v8, s76, v8
	s_nop 1
	s_mov_b64 s[90:91], vcc
	v_sub_f32_e32 v101, v125, v126
	v_sub_f32_e32 v102, v126, v128
	v_fma_f32 v101, v26, v101, v126
	v_sub_f32_e32 v105, v128, v130
	v_sub_f32_e32 v108, v129, v131
	v_fmac_f32_e32 v131, v27, v108
	v_fma_f32 v102, v26, v102, v128
	v_fmac_f32_e32 v130, v26, v105
	v_sub_f32_e32 v103, v127, v129
	v_fma_f32 v103, v27, v103, v129
	v_lshlrev_b32_e32 v76, 16, v76
	v_add_f32_e32 v76, -1.0, v76
	v_lshlrev_b32_e32 v78, 16, v78
	v_add_f32_e32 v78, -1.0, v78
	v_lshlrev_b32_e32 v106, 16, v106
	v_add_f32_e32 v106, -1.0, v106
	v_lshlrev_b32_e32 v109, 16, v116
	v_add_f32_e32 v109, -1.0, v109
	v_cndmask_b32_e64 v111, v111, 0, s[92:93]
	v_cndmask_b32_e64 v113, v114, 0, s[92:93]
	v_sub_f32_e32 v108, v111, v71
	v_add_f32_dpp v114, v104, v104 quad_perm:[1,0,3,2] row_mask:0xf bank_mask:0xf bound_ctrl:1
	v_sub_f32_e32 v111, v113, v125
	v_sub_f32_e32 v115, v71, v96
	v_add_f32_dpp v113, v114, v114 quad_perm:[2,3,0,1] row_mask:0xf bank_mask:0xf bound_ctrl:1
	v_fma_f32 v71, v25, v108, v71
	v_fma_f32 v108, v26, v111, v125
	v_fma_f32 v76, v20, v76, 1.0
	v_add_f32_dpp v111, v113, v113 row_half_mirror row_mask:0xf bank_mask:0xf bound_ctrl:1
	v_cndmask_b32_e64 v112, v112, 0, s[92:93]
	v_sub_f32_e32 v116, v97, v127
	v_add_f32_dpp v117, v94, v94 quad_perm:[1,0,3,2] row_mask:0xf bank_mask:0xf bound_ctrl:1
	v_sub_f32_e32 v118, v96, v95
	v_add_f32_dpp v119, v98, v98 quad_perm:[1,0,3,2] row_mask:0xf bank_mask:0xf bound_ctrl:1
	v_sub_f32_e32 v120, v95, v99
	v_fma_f32 v78, v20, v78, 1.0
	v_fma_f32 v106, v20, v106, 1.0
	v_fma_f32 v109, v20, v109, 1.0
	v_mul_f32_e32 v76, v76, v108
	v_add_f32_dpp v108, v111, v111 row_mirror row_mask:0xf bank_mask:0xf bound_ctrl:1
	v_sub_f32_e32 v112, v112, v97
	v_fma_f32 v96, v25, v115, v96
	v_fma_f32 v114, v27, v116, v127
	v_add_f32_dpp v115, v117, v117 quad_perm:[2,3,0,1] row_mask:0xf bank_mask:0xf bound_ctrl:1
	v_fma_f32 v95, v25, v118, v95
	v_add_f32_dpp v116, v119, v119 quad_perm:[2,3,0,1] row_mask:0xf bank_mask:0xf bound_ctrl:1
	v_fmac_f32_e32 v99, v25, v120
	v_mul_f32_e32 v78, v101, v78
	v_mul_f32_e32 v102, v102, v106
	v_mul_f32_e32 v109, v130, v109
	v_mov_b32_e32 v111, v108
	v_fma_f32 v97, v27, v112, v97
	v_add_f32_dpp v112, v115, v115 row_half_mirror row_mask:0xf bank_mask:0xf bound_ctrl:1
	v_add_f32_dpp v113, v116, v116 row_half_mirror row_mask:0xf bank_mask:0xf bound_ctrl:1
	v_mul_f32_e32 v78, v96, v78
	v_mul_f32_e32 v95, v95, v102
	v_mul_f32_e32 v99, v99, v109
	s_nop 1
	v_permlane16_swap_b32 v108, v111
	v_add_f32_dpp v101, v112, v112 row_mirror row_mask:0xf bank_mask:0xf bound_ctrl:1
	v_add_f32_dpp v106, v113, v113 row_mirror row_mask:0xf bank_mask:0xf bound_ctrl:1
	v_mul_f32_e32 v112, v21, v78
	v_mul_f32_e32 v113, v21, v95
	v_mul_f32_e32 v115, v21, v99
	v_add_f32_e32 v108, v108, v111
	v_mov_b32_dpp v111, v112 quad_perm:[1,0,3,2] row_mask:0xf bank_mask:0xf bound_ctrl:1
	v_mov_b32_dpp v112, v113 quad_perm:[1,0,3,2] row_mask:0xf bank_mask:0xf bound_ctrl:1
	v_mov_b32_dpp v113, v115 quad_perm:[1,0,3,2] row_mask:0xf bank_mask:0xf bound_ctrl:1
	v_mov_b32_e32 v115, v108
	s_nop 1
	v_permlane32_swap_b32 v108, v115
	v_mul_f32_e32 v71, v71, v76
	v_add_f32_e32 v108, v108, v115
	v_fmac_f32_e32 v104, 0xbc800000, v108
	v_mul_f32_e32 v108, v104, v104
	v_mul_f32_e32 v109, v21, v71
	v_lshlrev_b32_e32 v77, 16, v77
	v_mov_b32_dpp v108, v108 quad_perm:[1,0,3,2] row_mask:0xf bank_mask:0xf bound_ctrl:1
	v_fmac_f32_e32 v108, v104, v104
	v_mov_b32_dpp v109, v109 quad_perm:[1,0,3,2] row_mask:0xf bank_mask:0xf bound_ctrl:1
	v_fmac_f32_e32 v109, v21, v71
	v_add_f32_dpp v108, v108, v108 quad_perm:[2,3,0,1] row_mask:0xf bank_mask:0xf bound_ctrl:1
	v_mov_b32_e32 v76, v101
	v_add_f32_dpp v71, v109, v109 quad_perm:[2,3,0,1] row_mask:0xf bank_mask:0xf bound_ctrl:1
	v_add_f32_dpp v108, v108, v108 row_half_mirror row_mask:0xf bank_mask:0xf bound_ctrl:1
	v_fmac_f32_e32 v111, v21, v78
	v_add_f32_dpp v71, v71, v71 row_half_mirror row_mask:0xf bank_mask:0xf bound_ctrl:1
	v_add_f32_dpp v108, v108, v108 row_mirror row_mask:0xf bank_mask:0xf bound_ctrl:1
	v_mov_b32_e32 v115, v108
	s_nop 1
	v_permlane16_swap_b32 v108, v115
	v_add_f32_dpp v71, v71, v71 row_mirror row_mask:0xf bank_mask:0xf bound_ctrl:1
	v_add_f32_e32 v108, v108, v115
	v_mov_b32_e32 v115, v108
	v_mov_b32_e32 v109, v71
	s_nop 1
	v_permlane32_swap_b32 v108, v115
	s_nop 1
	v_permlane16_swap_b32 v71, v109
	v_add_f32_dpp v78, v111, v111 quad_perm:[2,3,0,1] row_mask:0xf bank_mask:0xf bound_ctrl:1
	v_add_f32_e32 v108, v108, v115
	v_add_f32_e32 v71, v71, v109
	v_fmamk_f32 v108, v108, 0x3c800000, v28
	v_mov_b32_e32 v109, v71
	v_mul_f32_e32 v115, 0x4f800000, v108
	v_cmp_gt_f32_e32 vcc, s78, v108
	s_nop 1
	v_permlane32_swap_b32 v71, v109
	v_add_f32_dpp v78, v78, v78 row_half_mirror row_mask:0xf bank_mask:0xf bound_ctrl:1
	v_add_f32_e32 v71, v71, v109
	v_cndmask_b32_e32 v108, v108, v115, vcc
	v_sqrt_f32_e32 v109, v108
	v_add_f32_dpp v78, v78, v78 row_mirror row_mask:0xf bank_mask:0xf bound_ctrl:1
	v_mov_b32_e32 v111, v78
	v_lshlrev_b32_e32 v79, 16, v79
	v_add_u32_e32 v115, -1, v109
	v_add_u32_e32 v116, 1, v109
	v_fma_f32 v117, -v115, v109, v108
	v_fma_f32 v118, -v116, v109, v108
	v_cmp_ge_f32_e64 s[6:7], 0, v117
	v_mov_b32_e32 v96, v106
	v_fmac_f32_e32 v112, v21, v95
	v_cndmask_b32_e64 v109, v109, v115, s[6:7]
	v_cmp_lt_f32_e64 s[6:7], 0, v118
	v_add_f32_dpp v95, v112, v112 quad_perm:[2,3,0,1] row_mask:0xf bank_mask:0xf bound_ctrl:1
	v_add_f32_dpp v105, v100, v100 quad_perm:[1,0,3,2] row_mask:0xf bank_mask:0xf bound_ctrl:1
	v_cndmask_b32_e64 v109, v109, v116, s[6:7]
	v_mul_f32_e32 v115, 0x37800000, v109
	v_cndmask_b32_e32 v109, v109, v115, vcc
	v_cmp_class_f32_e32 vcc, v108, v29
	v_add_f32_dpp v95, v95, v95 row_half_mirror row_mask:0xf bank_mask:0xf bound_ctrl:1
	v_lshlrev_b32_e32 v107, 16, v107
	v_cndmask_b32_e32 v108, v109, v108, vcc
	v_div_scale_f32 v109, s[6:7], v108, v108, 1.0
	v_rcp_f32_e32 v116, v109
	v_div_scale_f32 v115, vcc, 1.0, v108, 1.0
	v_add_f32_dpp v95, v95, v95 row_mirror row_mask:0xf bank_mask:0xf bound_ctrl:1
	v_fma_f32 v117, -v109, v116, 1.0
	v_fmac_f32_e32 v116, v117, v116
	v_mul_f32_e32 v117, v115, v116
	v_fma_f32 v118, -v109, v117, v115
	v_fmac_f32_e32 v117, v118, v116
	v_fma_f32 v109, -v109, v117, v115
	v_div_fmas_f32 v109, v109, v116, v117
	v_div_fixup_f32 v108, v109, v108, 1.0
	v_mul_f32_e32 v104, v104, v108
	v_fma_f32 v104, v22, v104, v23
	v_fmac_f32_e32 v104, v97, v71
	v_mul_f32_e32 v71, v104, v77
	v_mul_f32_e32 v71, v24, v71
	v_cvt_pk_bf16_f32 v71, v71, v71
	global_store_short v[92:93], v71, off
	s_nop 1
	v_permlane16_swap_b32 v76, v101
	v_mov_b32_e32 v112, v95
	v_add_f32_e32 v71, v76, v101
	v_mov_b32_e32 v76, v71
	s_nop 1
	v_permlane32_swap_b32 v76, v71
	v_add_f32_dpp v105, v105, v105 quad_perm:[2,3,0,1] row_mask:0xf bank_mask:0xf bound_ctrl:1
	v_add_f32_e32 v71, v76, v71
	v_fmac_f32_e32 v94, 0xbc800000, v71
	v_mul_f32_e32 v71, v94, v94
	v_add_f32_dpp v105, v105, v105 row_half_mirror row_mask:0xf bank_mask:0xf bound_ctrl:1
	v_fmac_f32_e32 v113, v21, v99
	v_mov_b32_dpp v71, v71 quad_perm:[1,0,3,2] row_mask:0xf bank_mask:0xf bound_ctrl:1
	v_fmac_f32_e32 v71, v94, v94
	v_add_f32_dpp v105, v105, v105 row_mirror row_mask:0xf bank_mask:0xf bound_ctrl:1
	v_mov_b32_e32 v102, v105
	v_add_f32_dpp v71, v71, v71 quad_perm:[2,3,0,1] row_mask:0xf bank_mask:0xf bound_ctrl:1
	v_add_f32_dpp v99, v113, v113 quad_perm:[2,3,0,1] row_mask:0xf bank_mask:0xf bound_ctrl:1
	v_lshlrev_b32_e32 v110, 16, v110
	v_add_f32_dpp v71, v71, v71 row_half_mirror row_mask:0xf bank_mask:0xf bound_ctrl:1
	v_add_f32_dpp v99, v99, v99 row_half_mirror row_mask:0xf bank_mask:0xf bound_ctrl:1
	s_nop 0
	v_add_f32_dpp v71, v71, v71 row_mirror row_mask:0xf bank_mask:0xf bound_ctrl:1
	v_mov_b32_e32 v76, v71
	s_nop 1
	v_permlane16_swap_b32 v76, v71
	v_add_f32_dpp v99, v99, v99 row_mirror row_mask:0xf bank_mask:0xf bound_ctrl:1
	v_add_f32_e32 v71, v76, v71
	v_mov_b32_e32 v76, v71
	s_nop 1
	v_permlane32_swap_b32 v76, v71
	s_nop 1
	v_permlane16_swap_b32 v111, v78
	v_mov_b32_e32 v113, v99
	v_add_f32_e32 v71, v76, v71
	v_add_f32_e32 v76, v111, v78
	v_fmamk_f32 v71, v71, 0x3c800000, v28
	v_mov_b32_e32 v77, v76
	v_mul_f32_e32 v78, 0x4f800000, v71
	v_cmp_gt_f32_e32 vcc, s78, v71
	s_nop 1
	v_permlane32_swap_b32 v77, v76
	s_nop 0
	v_add_f32_e32 v76, v77, v76
	v_cndmask_b32_e32 v71, v71, v78, vcc
	v_sqrt_f32_e32 v77, v71
	s_nop 0
	v_add_u32_e32 v78, -1, v77
	v_add_u32_e32 v92, 1, v77
	v_fma_f32 v93, -v78, v77, v71
	v_fma_f32 v97, -v92, v77, v71
	v_cmp_ge_f32_e64 s[6:7], 0, v93
	s_nop 1
	v_cndmask_b32_e64 v77, v77, v78, s[6:7]
	v_cmp_lt_f32_e64 s[6:7], 0, v97
	s_nop 1
	v_cndmask_b32_e64 v77, v77, v92, s[6:7]
	v_mul_f32_e32 v78, 0x37800000, v77
	v_cndmask_b32_e32 v77, v77, v78, vcc
	v_cmp_class_f32_e32 vcc, v71, v29
	s_nop 1
	v_cndmask_b32_e32 v71, v77, v71, vcc
	v_div_scale_f32 v77, s[6:7], v71, v71, 1.0
	v_rcp_f32_e32 v92, v77
	v_div_scale_f32 v78, vcc, 1.0, v71, 1.0
	v_fma_f32 v93, -v77, v92, 1.0
	v_fmac_f32_e32 v92, v93, v92
	v_mul_f32_e32 v93, v78, v92
	v_fma_f32 v97, -v77, v93, v78
	v_fmac_f32_e32 v93, v97, v92
	v_fma_f32 v77, -v77, v93, v78
	v_div_fmas_f32 v77, v77, v92, v93
	v_div_fixup_f32 v71, v77, v71, 1.0
	v_mul_f32_e32 v71, v94, v71
	v_fma_f32 v71, v22, v71, v23
	v_fmac_f32_e32 v71, v114, v76
	v_mul_f32_e32 v71, v71, v79
	v_mul_f32_e32 v71, v24, v71
	v_cvt_pk_bf16_f32 v71, v71, v71
	global_store_short v[122:123], v71, off
	s_nop 1
	v_permlane16_swap_b32 v106, v96
	s_nop 0
	v_add_f32_e32 v71, v106, v96
	v_mov_b32_e32 v76, v71
	s_nop 1
	v_permlane32_swap_b32 v71, v76
	s_nop 0
	v_add_f32_e32 v71, v71, v76
	v_fmac_f32_e32 v98, 0xbc800000, v71
	v_mul_f32_e32 v71, v98, v98
	s_nop 1
	v_mov_b32_dpp v71, v71 quad_perm:[1,0,3,2] row_mask:0xf bank_mask:0xf bound_ctrl:1
	v_fmac_f32_e32 v71, v98, v98
	s_nop 1
	v_add_f32_dpp v71, v71, v71 quad_perm:[2,3,0,1] row_mask:0xf bank_mask:0xf bound_ctrl:1
	s_nop 1
	v_add_f32_dpp v71, v71, v71 row_half_mirror row_mask:0xf bank_mask:0xf bound_ctrl:1
	s_nop 1
	v_add_f32_dpp v71, v71, v71 row_mirror row_mask:0xf bank_mask:0xf bound_ctrl:1
	v_mov_b32_e32 v76, v71
	s_nop 1
	v_permlane16_swap_b32 v71, v76
	s_nop 0
	v_add_f32_e32 v71, v71, v76
	v_mov_b32_e32 v76, v71
	s_nop 1
	v_permlane32_swap_b32 v71, v76
	s_nop 1
	v_permlane16_swap_b32 v95, v112
	s_nop 0
	v_add_f32_e32 v71, v71, v76
	v_add_f32_e32 v76, v95, v112
	v_fmamk_f32 v71, v71, 0x3c800000, v28
	v_mov_b32_e32 v77, v76
	v_mul_f32_e32 v78, 0x4f800000, v71
	v_cmp_gt_f32_e32 vcc, s78, v71
	s_nop 1
	v_permlane32_swap_b32 v76, v77
	s_nop 0
	v_add_f32_e32 v76, v76, v77
	v_cndmask_b32_e32 v71, v71, v78, vcc
	v_sqrt_f32_e32 v77, v71
	s_nop 0
	v_add_u32_e32 v78, -1, v77
	v_add_u32_e32 v79, 1, v77
	v_fma_f32 v92, -v78, v77, v71
	v_fma_f32 v93, -v79, v77, v71
	v_cmp_ge_f32_e64 s[6:7], 0, v92
	s_nop 1
	v_cndmask_b32_e64 v77, v77, v78, s[6:7]
	v_cmp_lt_f32_e64 s[6:7], 0, v93
	s_nop 1
	v_cndmask_b32_e64 v77, v77, v79, s[6:7]
	v_mul_f32_e32 v78, 0x37800000, v77
	v_cndmask_b32_e32 v77, v77, v78, vcc
	v_cmp_class_f32_e32 vcc, v71, v29
	s_nop 1
	v_cndmask_b32_e32 v71, v77, v71, vcc
	v_div_scale_f32 v77, s[6:7], v71, v71, 1.0
	v_rcp_f32_e32 v79, v77
	v_div_scale_f32 v78, vcc, 1.0, v71, 1.0
	v_fma_f32 v92, -v77, v79, 1.0
	v_fmac_f32_e32 v79, v92, v79
	v_mul_f32_e32 v92, v78, v79
	v_fma_f32 v93, -v77, v92, v78
	v_fmac_f32_e32 v92, v93, v79
	v_fma_f32 v77, -v77, v92, v78
	v_div_fmas_f32 v77, v77, v79, v92
	v_div_fixup_f32 v71, v77, v71, 1.0
	v_mul_f32_e32 v71, v98, v71
	v_fma_f32 v71, v22, v71, v23
	v_fmac_f32_e32 v71, v103, v76
	v_mul_f32_e32 v71, v71, v107
	v_mul_f32_e32 v71, v24, v71
	v_cvt_pk_bf16_f32 v71, v71, v71
	global_store_short v[74:75], v71, off
	s_nop 1
	v_permlane16_swap_b32 v105, v102
	s_nop 0
	v_add_f32_e32 v71, v105, v102
	v_mov_b32_e32 v74, v71
	s_nop 1
	v_permlane32_swap_b32 v71, v74
	s_nop 0
	v_add_f32_e32 v71, v71, v74
	v_fmac_f32_e32 v100, 0xbc800000, v71
	v_mul_f32_e32 v71, v100, v100
	s_nop 1
	v_mov_b32_dpp v71, v71 quad_perm:[1,0,3,2] row_mask:0xf bank_mask:0xf bound_ctrl:1
	v_fmac_f32_e32 v71, v100, v100
	s_nop 1
	v_add_f32_dpp v71, v71, v71 quad_perm:[2,3,0,1] row_mask:0xf bank_mask:0xf bound_ctrl:1
	s_nop 1
	v_add_f32_dpp v71, v71, v71 row_half_mirror row_mask:0xf bank_mask:0xf bound_ctrl:1
	s_nop 1
	v_add_f32_dpp v71, v71, v71 row_mirror row_mask:0xf bank_mask:0xf bound_ctrl:1
	v_mov_b32_e32 v74, v71
	s_nop 1
	v_permlane16_swap_b32 v71, v74
	s_nop 0
	v_add_f32_e32 v71, v71, v74
	v_mov_b32_e32 v74, v71
	s_nop 1
	v_permlane32_swap_b32 v71, v74
	s_nop 1
	v_permlane16_swap_b32 v99, v113
	s_nop 0
	v_add_f32_e32 v71, v71, v74
	v_add_f32_e32 v74, v99, v113
	v_fmamk_f32 v71, v71, 0x3c800000, v28
	v_mov_b32_e32 v75, v74
	v_mul_f32_e32 v76, 0x4f800000, v71
	v_cmp_gt_f32_e32 vcc, s78, v71
	s_nop 1
	v_permlane32_swap_b32 v74, v75
	s_nop 0
	v_add_f32_e32 v74, v74, v75
	v_cndmask_b32_e32 v71, v71, v76, vcc
	v_sqrt_f32_e32 v75, v71
	s_nop 0
	v_add_u32_e32 v76, -1, v75
	v_add_u32_e32 v77, 1, v75
	v_fma_f32 v78, -v76, v75, v71
	v_fma_f32 v79, -v77, v75, v71
	v_cmp_ge_f32_e64 s[6:7], 0, v78
	s_nop 1
	v_cndmask_b32_e64 v75, v75, v76, s[6:7]
	v_cmp_lt_f32_e64 s[6:7], 0, v79
	s_nop 1
	v_cndmask_b32_e64 v75, v75, v77, s[6:7]
	v_mul_f32_e32 v76, 0x37800000, v75
	v_cndmask_b32_e32 v75, v75, v76, vcc
	v_cmp_class_f32_e32 vcc, v71, v29
	s_nop 1
	v_cndmask_b32_e32 v71, v75, v71, vcc
	v_div_scale_f32 v75, s[6:7], v71, v71, 1.0
	v_rcp_f32_e32 v76, v75
	v_div_scale_f32 v77, vcc, 1.0, v71, 1.0
	v_fma_f32 v78, -v75, v76, 1.0
	v_fmac_f32_e32 v76, v78, v76
	v_mul_f32_e32 v78, v77, v76
	v_fma_f32 v79, -v75, v78, v77
	v_fmac_f32_e32 v78, v79, v76
	v_fma_f32 v75, -v75, v78, v77
	v_div_fmas_f32 v75, v75, v76, v78
	v_div_fixup_f32 v71, v75, v71, 1.0
	v_mul_f32_e32 v71, v100, v71
	v_fma_f32 v71, v22, v71, v23
	v_fmac_f32_e32 v71, v131, v74
	v_mul_f32_e32 v71, v71, v110
	v_mul_f32_e32 v71, v24, v71
	v_cvt_pk_bf16_f32 v71, v71, v71
	global_store_short v[72:73], v71, off
	s_add_u32 s88, s88, 1
	s_cmp_lt_u32 s88, 16
	s_cbranch_scc1 .Lgn_loop
	s_waitcnt vmcnt(0)
